# quarter-unit K loop: MFMAs of the previous K step spread over three of the four barrier phases, LDS-DMA refill moved to the fourth phase (after both wave groups' read waits), vmcnt(0) in phase three
# speedup vs baseline: 1.0026x; 1.0026x over previous
.Lq5_top:
	ds_read_b128 v[148:151], v214
	ds_read_b128 v[152:155], v214 offset:1024
	ds_read_b128 v[156:159], v214 offset:2048
	ds_read_b128 v[160:163], v214 offset:3072
	v_lshl_add_u64 v[2:3], s[34:35], 0, v[200:201]
	s_add_i32 m0, s48, 0xc000
	ds_read_b128 v[188:191], v216
	ds_read_b128 v[192:195], v216 offset:1024
	ds_read_b128 v[180:183], v216 offset:2048
	ds_read_b128 v[184:187], v216 offset:3072
	ds_read_b128 v[172:175], v216 offset:4096
	ds_read_b128 v[176:179], v216 offset:5120
	ds_read_b128 v[164:167], v216 offset:6144
	ds_read_b128 v[168:171], v216 offset:7168
	v_lshl_add_u64 v[2:3], s[34:35], 0, v[202:203]
	s_add_i32 m0, s48, 0xe000
	s_nop 0
	s_setprio 1
	v_mfma_f32_16x16x32_bf16 v[128:131], v[4:7], v[44:47], v[128:131]
	v_mfma_f32_16x16x32_bf16 v[124:127], v[12:15], v[44:47], v[124:127]
	v_mfma_f32_16x16x32_bf16 v[120:123], v[4:7], v[36:39], v[120:123]
	v_mfma_f32_16x16x32_bf16 v[116:119], v[12:15], v[36:39], v[116:119]
	v_mfma_f32_16x16x32_bf16 v[104:107], v[4:7], v[28:31], v[104:107]
	v_mfma_f32_16x16x32_bf16 v[100:103], v[12:15], v[28:31], v[100:103]
	s_setprio 0
	s_barrier
	v_cmp_ne_u32_e64 s[2:3], 1, v217
	s_andn2_b64 vcc, exec, s[26:27]
	s_add_u32 s56, s34, 0xfff80080
	s_addc_u32 s57, s35, -1
	s_cmp_eq_u32 s77, 12
	s_cselect_b32 s59, s39, s57
	s_cselect_b32 s58, s38, s56
	s_cselect_b32 s57, s47, s41
	s_cselect_b32 s56, s46, s18
	s_setprio 1
	v_mfma_f32_16x16x32_bf16 v[88:91], v[4:7], v[20:23], v[88:91]
	v_mfma_f32_16x16x32_bf16 v[84:87], v[12:15], v[20:23], v[84:87]
	v_mfma_f32_16x16x32_bf16 v[128:131], v[8:11], v[48:51], v[128:131]
	v_mfma_f32_16x16x32_bf16 v[124:127], v[16:19], v[48:51], v[124:127]
	v_mfma_f32_16x16x32_bf16 v[120:123], v[8:11], v[40:43], v[120:123]
	v_mfma_f32_16x16x32_bf16 v[116:119], v[16:19], v[40:43], v[116:119]
	s_setprio 0
	s_waitcnt lgkmcnt(0)
	s_barrier
	s_setprio 1
	v_mfma_f32_16x16x32_bf16 v[104:107], v[8:11], v[32:35], v[104:107]
	v_mfma_f32_16x16x32_bf16 v[100:103], v[16:19], v[32:35], v[100:103]
	v_mfma_f32_16x16x32_bf16 v[88:91], v[8:11], v[24:27], v[88:91]
	v_mfma_f32_16x16x32_bf16 v[84:87], v[16:19], v[24:27], v[84:87]
	s_setprio 0
	s_waitcnt vmcnt(0)
	s_barrier
	s_mov_b32 m0, s49
	v_lshl_add_u64 v[2:3], s[56:57], 0, v[198:199]
	s_add_u32 s78, s56, 0x80000
	global_load_lds_dwordx4 v[2:3], off
	v_lshl_add_u64 v[204:205], s[56:57], 0, v[196:197]
	s_mov_b32 m0, s50
	s_addc_u32 s79, s57, 0
	global_load_lds_dwordx4 v[204:205], off
	v_lshl_add_u64 v[206:207], s[78:79], 0, v[198:199]
	s_mov_b32 m0, s51
	v_lshl_add_u64 v[208:209], s[58:59], 0, v[196:197]
	v_lshl_add_u64 v[206:207], s[78:79], 0, v[196:197]
	s_mov_b32 m0, s60
	s_and_b64 vcc, exec, s[2:3]
	v_lshl_add_u64 v[206:207], s[58:59], 0, v[198:199]
	s_mov_b32 m0, s48
	s_nop 0
	global_load_lds_dwordx4 v[206:207], off
	s_mov_b32 m0, s61
	s_nop 0
	global_load_lds_dwordx4 v[208:209], off
	s_barrier
	v_add_u32_e32 v1, 0x18000, v213
	ds_read_b128 v[4:7], v1
	ds_read_b128 v[8:11], v1 offset:1024
	ds_read_b128 v[12:15], v1 offset:2048
	ds_read_b128 v[16:19], v1 offset:3072
	v_add_u32_e32 v1, 0x1c000, v213
	s_add_u32 s58, s58, 0x80000
	s_addc_u32 s59, s59, 0
	s_mov_b32 m0, s62
	v_lshl_add_u64 v[218:219], s[58:59], 0, v[198:199]
	ds_read_b128 v[44:47], v216 offset:32768
	ds_read_b128 v[48:51], v216 offset:33792
	ds_read_b128 v[36:39], v216 offset:34816
	ds_read_b128 v[40:43], v216 offset:35840
	ds_read_b128 v[28:31], v216 offset:36864
	ds_read_b128 v[32:35], v216 offset:37888
	ds_read_b128 v[20:23], v216 offset:38912
	ds_read_b128 v[24:27], v216 offset:39936
	v_lshl_add_u64 v[218:219], s[58:59], 0, v[196:197]
	s_mov_b32 m0, s63
	s_nop 0
	s_setprio 1
	v_mfma_f32_16x16x32_bf16 v[128:131], v[148:151], v[188:191], v[128:131]
	v_mfma_f32_16x16x32_bf16 v[124:127], v[156:159], v[188:191], v[124:127]
	v_mfma_f32_16x16x32_bf16 v[120:123], v[148:151], v[180:183], v[120:123]
	v_mfma_f32_16x16x32_bf16 v[116:119], v[156:159], v[180:183], v[116:119]
	v_mfma_f32_16x16x32_bf16 v[104:107], v[148:151], v[172:175], v[104:107]
	v_mfma_f32_16x16x32_bf16 v[100:103], v[156:159], v[172:175], v[100:103]
	s_setprio 0
	s_barrier
	s_and_b64 vcc, exec, s[2:3]
	s_setprio 1
	v_mfma_f32_16x16x32_bf16 v[88:91], v[148:151], v[164:167], v[88:91]
	v_mfma_f32_16x16x32_bf16 v[84:87], v[156:159], v[164:167], v[84:87]
	v_mfma_f32_16x16x32_bf16 v[128:131], v[152:155], v[192:195], v[128:131]
	v_mfma_f32_16x16x32_bf16 v[124:127], v[160:163], v[192:195], v[124:127]
	v_mfma_f32_16x16x32_bf16 v[120:123], v[152:155], v[184:187], v[120:123]
	v_mfma_f32_16x16x32_bf16 v[116:119], v[160:163], v[184:187], v[116:119]
	s_setprio 0
	s_waitcnt lgkmcnt(0)
	s_barrier
	s_setprio 1
	v_mfma_f32_16x16x32_bf16 v[104:107], v[152:155], v[176:179], v[104:107]
	v_mfma_f32_16x16x32_bf16 v[100:103], v[160:163], v[176:179], v[100:103]
	v_mfma_f32_16x16x32_bf16 v[88:91], v[152:155], v[168:171], v[88:91]
	v_mfma_f32_16x16x32_bf16 v[84:87], v[160:163], v[168:171], v[84:87]
	s_setprio 0
	s_waitcnt vmcnt(0)
	s_barrier
	s_mov_b32 m0, s66
	v_lshl_add_u64 v[2:3], v[2:3], 0, s[16:17]
	s_add_u32 s56, s56, 0x80080
	global_load_lds_dwordx4 v[2:3], off
	v_lshl_add_u64 v[2:3], v[204:205], 0, s[16:17]
	s_mov_b32 m0, s67
	s_addc_u32 s57, s57, 0
	global_load_lds_dwordx4 v[2:3], off
	v_lshl_add_u64 v[2:3], s[56:57], 0, v[198:199]
	s_mov_b32 m0, s70
	s_and_b64 vcc, exec, s[2:3]
	v_lshl_add_u64 v[2:3], s[56:57], 0, v[196:197]
	s_mov_b32 m0, s71
	s_nop 0
	v_lshl_add_u64 v[2:3], v[206:207], 0, s[16:17]
	s_mov_b32 m0, s68
	s_nop 0
	global_load_lds_dwordx4 v[2:3], off
	v_lshl_add_u64 v[2:3], v[208:209], 0, s[16:17]
	s_mov_b32 m0, s69
	s_nop 0
	global_load_lds_dwordx4 v[2:3], off
	s_branch .Lq5_be

.Lq6_top:
	ds_read_b128 v[180:183], v247
	ds_read_b128 v[184:187], v247 offset:1024
	ds_read_b128 v[188:191], v247 offset:2048
	ds_read_b128 v[192:195], v247 offset:3072
	v_lshl_add_u64 v[2:3], s[38:39], 0, v[232:233]
	s_add_i32 m0, s44, 0xc000
	ds_read_b128 v[220:223], v249
	ds_read_b128 v[224:227], v249 offset:1024
	ds_read_b128 v[212:215], v249 offset:2048
	ds_read_b128 v[216:219], v249 offset:3072
	ds_read_b128 v[204:207], v249 offset:4096
	ds_read_b128 v[208:211], v249 offset:5120
	ds_read_b128 v[196:199], v249 offset:6144
	ds_read_b128 v[200:203], v249 offset:7168
	v_lshl_add_u64 v[2:3], s[38:39], 0, v[234:235]
	s_add_i32 m0, s44, 0xe000
	s_nop 0
	s_setprio 1
	v_mfma_f32_16x16x32_bf16 v[68:71], v[4:7], v[44:47], v[160:163]
	v_mfma_f32_16x16x32_bf16 v[72:75], v[12:15], v[44:47], v[156:159]
	v_mfma_f32_16x16x32_bf16 v[76:79], v[4:7], v[36:39], v[152:155]
	v_mfma_f32_16x16x32_bf16 v[80:83], v[12:15], v[36:39], v[148:151]
	v_mfma_f32_16x16x32_bf16 v[84:87], v[4:7], v[28:31], v[136:139]
	v_mfma_f32_16x16x32_bf16 v[92:95], v[12:15], v[28:31], v[132:135]
	s_setprio 0
	s_barrier
	v_cmp_ne_u32_e64 s[4:5], 1, v251
	s_andn2_b64 vcc, exec, s[34:35]
	s_add_u32 s40, s38, 0xfff80080
	s_addc_u32 s41, s39, -1
	s_cmp_eq_u32 s84, 28
	s_cselect_b32 s47, s29, s41
	s_cselect_b32 s46, s28, s40
	s_cselect_b32 s41, s37, s27
	s_cselect_b32 s40, s36, s16
	s_setprio 1
	v_mfma_f32_16x16x32_bf16 v[96:99], v[4:7], v[20:23], v[120:123]
	v_mfma_f32_16x16x32_bf16 v[100:103], v[12:15], v[20:23], v[112:115]
	v_mfma_f32_16x16x32_bf16 v[68:71], v[8:11], v[48:51], v[68:71]
	v_mfma_f32_16x16x32_bf16 v[72:75], v[16:19], v[48:51], v[72:75]
	v_mfma_f32_16x16x32_bf16 v[76:79], v[8:11], v[40:43], v[76:79]
	v_mfma_f32_16x16x32_bf16 v[80:83], v[16:19], v[40:43], v[80:83]
	s_setprio 0
	s_waitcnt lgkmcnt(0)
	s_barrier
	s_setprio 1
	v_mfma_f32_16x16x32_bf16 v[84:87], v[8:11], v[32:35], v[84:87]
	v_mfma_f32_16x16x32_bf16 v[92:95], v[16:19], v[32:35], v[92:95]
	v_mfma_f32_16x16x32_bf16 v[96:99], v[8:11], v[24:27], v[96:99]
	v_mfma_f32_16x16x32_bf16 v[100:103], v[16:19], v[24:27], v[100:103]
	s_setprio 0
	s_waitcnt vmcnt(0)
	s_barrier
	s_mov_b32 m0, s45
	v_lshl_add_u64 v[2:3], s[40:41], 0, v[230:231]
	s_add_u32 s86, s40, 0x80000
	global_load_lds_dwordx4 v[2:3], off
	v_lshl_add_u64 v[236:237], s[40:41], 0, v[228:229]
	s_mov_b32 m0, s48
	s_addc_u32 s87, s41, 0
	global_load_lds_dwordx4 v[236:237], off
	v_lshl_add_u64 v[54:55], s[86:87], 0, v[230:231]
	s_mov_b32 m0, s49
	v_lshl_add_u64 v[238:239], s[46:47], 0, v[230:231]
	v_lshl_add_u64 v[54:55], s[86:87], 0, v[228:229]
	s_mov_b32 m0, s50
	v_lshl_add_u64 v[240:241], s[46:47], 0, v[228:229]
	s_mov_b32 m0, s44
	s_and_b64 vcc, exec, s[4:5]
	global_load_lds_dwordx4 v[238:239], off
	s_mov_b32 m0, s51
	s_nop 0
	global_load_lds_dwordx4 v[240:241], off
	s_barrier
	v_add_u32_e32 v1, 0x18000, v246
	ds_read_b128 v[4:7], v1
	ds_read_b128 v[8:11], v1 offset:1024
	ds_read_b128 v[12:15], v1 offset:2048
	ds_read_b128 v[16:19], v1 offset:3072
	v_add_u32_e32 v1, 0x1c000, v246
	s_add_u32 s46, s46, 0x80000
	s_addc_u32 s47, s47, 0
	s_mov_b32 m0, s56
	v_lshl_add_u64 v[112:113], s[46:47], 0, v[230:231]
	ds_read_b128 v[44:47], v249 offset:32768
	ds_read_b128 v[48:51], v249 offset:33792
	ds_read_b128 v[36:39], v249 offset:34816
	ds_read_b128 v[40:43], v249 offset:35840
	ds_read_b128 v[28:31], v249 offset:36864
	ds_read_b128 v[32:35], v249 offset:37888
	ds_read_b128 v[20:23], v249 offset:38912
	ds_read_b128 v[24:27], v249 offset:39936
	v_lshl_add_u64 v[112:113], s[46:47], 0, v[228:229]
	s_mov_b32 m0, s57
	s_nop 0
	s_setprio 1
	v_mfma_f32_16x16x32_bf16 v[68:71], v[180:183], v[220:223], v[68:71]
	v_mfma_f32_16x16x32_bf16 v[160:163], v[184:187], v[224:227], v[68:71]
	v_mfma_f32_16x16x32_bf16 v[68:71], v[188:191], v[220:223], v[72:75]
	v_mfma_f32_16x16x32_bf16 v[156:159], v[192:195], v[224:227], v[68:71]
	v_mfma_f32_16x16x32_bf16 v[68:71], v[180:183], v[212:215], v[76:79]
	v_mfma_f32_16x16x32_bf16 v[152:155], v[184:187], v[216:219], v[68:71]
	s_setprio 0
	s_barrier
	s_and_b64 vcc, exec, s[4:5]
	s_setprio 1
	v_mfma_f32_16x16x32_bf16 v[68:71], v[188:191], v[212:215], v[80:83]
	v_mfma_f32_16x16x32_bf16 v[148:151], v[192:195], v[216:219], v[68:71]
	v_mfma_f32_16x16x32_bf16 v[68:71], v[180:183], v[204:207], v[84:87]
	v_mfma_f32_16x16x32_bf16 v[136:139], v[184:187], v[208:211], v[68:71]
	v_mfma_f32_16x16x32_bf16 v[68:71], v[188:191], v[204:207], v[92:95]
	v_mfma_f32_16x16x32_bf16 v[132:135], v[192:195], v[208:211], v[68:71]
	s_setprio 0
	s_waitcnt lgkmcnt(0)
	s_barrier
	s_setprio 1
	v_mfma_f32_16x16x32_bf16 v[68:71], v[180:183], v[196:199], v[96:99]
	v_mfma_f32_16x16x32_bf16 v[120:123], v[184:187], v[200:203], v[68:71]
	v_mfma_f32_16x16x32_bf16 v[68:71], v[188:191], v[196:199], v[100:103]
	v_mfma_f32_16x16x32_bf16 v[112:115], v[192:195], v[200:203], v[68:71]
	s_setprio 0
	s_waitcnt vmcnt(0)
	s_barrier
	s_mov_b32 m0, s61
	v_lshl_add_u64 v[2:3], v[2:3], 0, s[14:15]
	s_add_u32 s40, s40, 0x80080
	global_load_lds_dwordx4 v[2:3], off
	v_lshl_add_u64 v[2:3], v[236:237], 0, s[14:15]
	s_mov_b32 m0, s62
	s_addc_u32 s41, s41, 0
	global_load_lds_dwordx4 v[2:3], off
	v_lshl_add_u64 v[2:3], s[40:41], 0, v[230:231]
	s_mov_b32 m0, s65
	s_and_b64 vcc, exec, s[4:5]
	v_lshl_add_u64 v[2:3], s[40:41], 0, v[228:229]
	s_mov_b32 m0, s66
	s_nop 0
	v_lshl_add_u64 v[2:3], v[238:239], 0, s[14:15]
	s_mov_b32 m0, s63
	s_nop 0
	global_load_lds_dwordx4 v[2:3], off
	v_lshl_add_u64 v[2:3], v[240:241], 0, s[14:15]
	s_mov_b32 m0, s64
	s_nop 0
	global_load_lds_dwordx4 v[2:3], off
	s_branch .Lq6_be
